# byte-phase pin: s_nop padding in front of the hot loop heads (4 GEMM K-loops, attention main/band loops, cross-attention unit loop) restores their baseline offsets within the 64-byte fetch line
# baseline (speedup 1.0000x reference)
; template <class Epi, class Sched, bool ALIGN_EPI = false, bool SP2 = false>
; __device__ __forceinline__ void gemm_phase(PG8_LAS unsigned char* lds, const Gemm g, const Sched& S, const Epi& E) {
;     ...
;         const char* nA = has_next ? (const char*)g.A + (size_t)nxt.pm * tstep : cA; const char* nB = has_next ? (const char*)g.Bt + (size_t)nxt.pn * tstep : cB;
;         for (int t = 0; t < nt; t += 2) {
;             const bool last = (t == nt - 2);
;             const char* a1 = cA + (size_t)(t + 1) * kstep;
;             const char* a2 = last ? nA : cA + (size_t)(t + 2) * kstep; const char* b2 = last ? nB : cB + (size_t)(t + 2) * kstep;
;     ...
;         for (int a = 0; a < 2; ++a)
; #pragma unroll
;             for (int b = 0; b < 2; ++b)
; #pragma unroll
;                 for (int m = 0; m < 4; ++m)
; #pragma unroll
;                     for (int n = 0; n < 2; ++n) acc[a][b][m][n] = (f32x4){0.f, 0.f, 0.f, 0.f};
.LBB0_241:
	s_ashr_i32 s79, s78, 31
	s_lshl_b64 s[54:55], s[78:79], 19
	s_add_u32 s80, s58, s54
	s_addc_u32 s81, s59, s55
	s_and_b64 s[54:55], s[4:5], exec
	s_cselect_b32 s49, s81, s87
	s_cselect_b32 s54, s80, s86
	s_ashr_i32 s77, s76, 31
	s_lshl_b64 s[64:65], s[76:77], 19
	s_add_u32 s82, s15, s64
	s_addc_u32 s83, s20, s65
	s_and_b64 s[64:65], s[4:5], exec
	s_cselect_b32 s55, s83, s89
	s_cselect_b32 s61, s82, s88
	s_add_u32 s86, s86, 0x40080
	s_addc_u32 s87, s87, 0
	s_add_u32 s64, s88, 0x100
	v_mov_b32_e32 v2, 0
	s_addc_u32 s65, s89, 0
	s_mov_b32 s77, -2
	v_mov_b32_e32 v3, v2
	v_mov_b32_e32 v4, v2
	v_mov_b32_e32 v5, v2
	v_mov_b32_e32 v6, v2
	v_mov_b32_e32 v7, v2
	v_mov_b32_e32 v8, v2
	v_mov_b32_e32 v9, v2
	v_mov_b32_e32 v18, v2
	v_mov_b32_e32 v19, v2
	v_mov_b32_e32 v20, v2
	v_mov_b32_e32 v21, v2
	v_mov_b32_e32 v22, v2
	v_mov_b32_e32 v23, v2
	v_mov_b32_e32 v24, v2
	v_mov_b32_e32 v25, v2
	s_waitcnt vmcnt(0)
	v_mov_b32_e32 v34, v2
	v_mov_b32_e32 v35, v2
	v_mov_b32_e32 v36, v2
	v_mov_b32_e32 v37, v2
	v_mov_b32_e32 v38, v2
	v_mov_b32_e32 v39, v2
	v_mov_b32_e32 v40, v2
	v_mov_b32_e32 v41, v2
	v_mov_b32_e32 v50, v2
	v_mov_b32_e32 v51, v2
	v_mov_b32_e32 v52, v2
	v_mov_b32_e32 v53, v2
	v_mov_b32_e32 v54, v2
	v_mov_b32_e32 v55, v2
	v_mov_b32_e32 v56, v2
	v_mov_b32_e32 v57, v2
	v_mov_b32_e32 v10, v2
	v_mov_b32_e32 v11, v2
	v_mov_b32_e32 v12, v2
	v_mov_b32_e32 v13, v2
	v_mov_b32_e32 v14, v2
	v_mov_b32_e32 v15, v2
	v_mov_b32_e32 v16, v2
	v_mov_b32_e32 v17, v2
	v_mov_b32_e32 v26, v2
	v_mov_b32_e32 v27, v2
	v_mov_b32_e32 v28, v2
	v_mov_b32_e32 v29, v2
	v_mov_b32_e32 v30, v2
	v_mov_b32_e32 v31, v2
	v_mov_b32_e32 v32, v2
	v_mov_b32_e32 v33, v2
	v_mov_b32_e32 v42, v2
	v_mov_b32_e32 v43, v2
	v_mov_b32_e32 v44, v2
	v_mov_b32_e32 v45, v2
	v_mov_b32_e32 v46, v2
	v_mov_b32_e32 v47, v2
	v_mov_b32_e32 v48, v2
	v_mov_b32_e32 v49, v2
	v_mov_b32_e32 v58, v2
	v_mov_b32_e32 v59, v2
	v_mov_b32_e32 v60, v2
	v_mov_b32_e32 v61, v2
	v_mov_b32_e32 v62, v2
	v_mov_b32_e32 v63, v2
	v_mov_b32_e32 v64, v2
	v_mov_b32_e32 v65, v2
	v_mov_b32_e32 v66, v2
	v_mov_b32_e32 v67, v2
	v_mov_b32_e32 v68, v2
	v_mov_b32_e32 v69, v2
	v_mov_b32_e32 v70, v2
	v_mov_b32_e32 v71, v2
	v_mov_b32_e32 v72, v2
	v_mov_b32_e32 v73, v2
	v_mov_b32_e32 v82, v2
	v_mov_b32_e32 v83, v2
	v_mov_b32_e32 v84, v2
	v_mov_b32_e32 v85, v2
	v_mov_b32_e32 v86, v2
	v_mov_b32_e32 v87, v2
	v_mov_b32_e32 v88, v2
	v_mov_b32_e32 v89, v2
	v_mov_b32_e32 v98, v2
	v_mov_b32_e32 v99, v2
	v_mov_b32_e32 v100, v2
	v_mov_b32_e32 v101, v2
	v_mov_b32_e32 v102, v2
	v_mov_b32_e32 v103, v2
	v_mov_b32_e32 v104, v2
	v_mov_b32_e32 v105, v2
	v_mov_b32_e32 v114, v2
	v_mov_b32_e32 v115, v2
	v_mov_b32_e32 v116, v2
	v_mov_b32_e32 v117, v2
	v_mov_b32_e32 v118, v2
	v_mov_b32_e32 v119, v2
	v_mov_b32_e32 v120, v2
	v_mov_b32_e32 v121, v2
	v_mov_b32_e32 v74, v2
	v_mov_b32_e32 v75, v2
	v_mov_b32_e32 v76, v2
	v_mov_b32_e32 v77, v2
	v_mov_b32_e32 v78, v2
	v_mov_b32_e32 v79, v2
	v_mov_b32_e32 v80, v2
	v_mov_b32_e32 v81, v2
	v_mov_b32_e32 v90, v2
	v_mov_b32_e32 v91, v2
	v_mov_b32_e32 v92, v2
	v_mov_b32_e32 v93, v2
	v_mov_b32_e32 v94, v2
	v_mov_b32_e32 v95, v2
	v_mov_b32_e32 v96, v2
	v_mov_b32_e32 v97, v2
	v_mov_b32_e32 v106, v2
	v_mov_b32_e32 v107, v2
	v_mov_b32_e32 v108, v2
	v_mov_b32_e32 v109, v2
	v_mov_b32_e32 v110, v2
	v_mov_b32_e32 v111, v2
	v_mov_b32_e32 v112, v2
	v_mov_b32_e32 v113, v2
	v_mov_b32_e32 v122, v2
	v_mov_b32_e32 v123, v2
	v_mov_b32_e32 v124, v2
	v_mov_b32_e32 v125, v2
	v_mov_b32_e32 v126, v2
	v_mov_b32_e32 v127, v2
	v_mov_b32_e32 v128, v2
	v_mov_b32_e32 v129, v2
	s_nop 0
	s_nop 0
	s_nop 0
	s_nop 0
	s_nop 0
	s_nop 0
	s_nop 0
	s_nop 0
	s_nop 0

; template <class Epi, class Sched, bool ALIGN_EPI = false, bool SP2 = false>
; __device__ __forceinline__ void gemm_phase(PG8_LAS unsigned char* lds, const Gemm g, const Sched& S, const Epi& E) {
;     ...
;         for (int a = 0; a < 2; ++a)
; #pragma unroll
;             for (int b = 0; b < 2; ++b)
; #pragma unroll
;                 for (int m = 0; m < 4; ++m)
; #pragma unroll
;                     for (int n = 0; n < 2; ++n) acc[a][b][m][n] = (f32x4){0.f, 0.f, 0.f, 0.f};
.LBB0_319:
	s_add_u32 s86, s86, 0x80
	s_addc_u32 s87, s87, 0
	s_add_u32 s64, s88, 0x100
	v_mov_b32_e32 v2, 0
	s_addc_u32 s65, s89, 0
	s_mov_b32 s66, 0
	v_mov_b32_e32 v3, v2
	v_mov_b32_e32 v4, v2
	v_mov_b32_e32 v5, v2
	v_mov_b32_e32 v6, v2
	v_mov_b32_e32 v7, v2
	v_mov_b32_e32 v8, v2
	v_mov_b32_e32 v9, v2
	v_mov_b32_e32 v18, v2
	v_mov_b32_e32 v19, v2
	v_mov_b32_e32 v20, v2
	v_mov_b32_e32 v21, v2
	v_mov_b32_e32 v22, v2
	v_mov_b32_e32 v23, v2
	v_mov_b32_e32 v24, v2
	v_mov_b32_e32 v25, v2
	s_waitcnt vmcnt(0)
	v_mov_b32_e32 v34, v2
	v_mov_b32_e32 v35, v2
	v_mov_b32_e32 v36, v2
	v_mov_b32_e32 v37, v2
	v_mov_b32_e32 v38, v2
	v_mov_b32_e32 v39, v2
	v_mov_b32_e32 v40, v2
	v_mov_b32_e32 v41, v2
	v_mov_b32_e32 v50, v2
	v_mov_b32_e32 v51, v2
	v_mov_b32_e32 v52, v2
	v_mov_b32_e32 v53, v2
	v_mov_b32_e32 v54, v2
	v_mov_b32_e32 v55, v2
	v_mov_b32_e32 v56, v2
	v_mov_b32_e32 v57, v2
	v_mov_b32_e32 v10, v2
	v_mov_b32_e32 v11, v2
	v_mov_b32_e32 v12, v2
	v_mov_b32_e32 v13, v2
	v_mov_b32_e32 v14, v2
	v_mov_b32_e32 v15, v2
	v_mov_b32_e32 v16, v2
	v_mov_b32_e32 v17, v2
	v_mov_b32_e32 v26, v2
	v_mov_b32_e32 v27, v2
	v_mov_b32_e32 v28, v2
	v_mov_b32_e32 v29, v2
	v_mov_b32_e32 v30, v2
	v_mov_b32_e32 v31, v2
	v_mov_b32_e32 v32, v2
	v_mov_b32_e32 v33, v2
	v_mov_b32_e32 v42, v2
	v_mov_b32_e32 v43, v2
	v_mov_b32_e32 v44, v2
	v_mov_b32_e32 v45, v2
	v_mov_b32_e32 v46, v2
	v_mov_b32_e32 v47, v2
	v_mov_b32_e32 v48, v2
	v_mov_b32_e32 v49, v2
	v_mov_b32_e32 v58, v2
	v_mov_b32_e32 v59, v2
	v_mov_b32_e32 v60, v2
	v_mov_b32_e32 v61, v2
	v_mov_b32_e32 v62, v2
	v_mov_b32_e32 v63, v2
	v_mov_b32_e32 v64, v2
	v_mov_b32_e32 v65, v2
	v_mov_b32_e32 v66, v2
	v_mov_b32_e32 v67, v2
	v_mov_b32_e32 v68, v2
	v_mov_b32_e32 v69, v2
	v_mov_b32_e32 v70, v2
	v_mov_b32_e32 v71, v2
	v_mov_b32_e32 v72, v2
	v_mov_b32_e32 v73, v2
	v_mov_b32_e32 v82, v2
	v_mov_b32_e32 v83, v2
	v_mov_b32_e32 v84, v2
	v_mov_b32_e32 v85, v2
	v_mov_b32_e32 v86, v2
	v_mov_b32_e32 v87, v2
	v_mov_b32_e32 v88, v2
	v_mov_b32_e32 v89, v2
	v_mov_b32_e32 v98, v2
	v_mov_b32_e32 v99, v2
	v_mov_b32_e32 v100, v2
	v_mov_b32_e32 v101, v2
	v_mov_b32_e32 v102, v2
	v_mov_b32_e32 v103, v2
	v_mov_b32_e32 v104, v2
	v_mov_b32_e32 v105, v2
	v_mov_b32_e32 v118, v2
	v_mov_b32_e32 v119, v2
	v_mov_b32_e32 v120, v2
	v_mov_b32_e32 v121, v2
	v_mov_b32_e32 v134, v2
	v_mov_b32_e32 v135, v2
	v_mov_b32_e32 v136, v2
	v_mov_b32_e32 v137, v2
	v_mov_b32_e32 v74, v2
	v_mov_b32_e32 v75, v2
	v_mov_b32_e32 v76, v2
	v_mov_b32_e32 v77, v2
	v_mov_b32_e32 v78, v2
	v_mov_b32_e32 v79, v2
	v_mov_b32_e32 v80, v2
	v_mov_b32_e32 v81, v2
	v_mov_b32_e32 v90, v2
	v_mov_b32_e32 v91, v2
	v_mov_b32_e32 v92, v2
	v_mov_b32_e32 v93, v2
	v_mov_b32_e32 v94, v2
	v_mov_b32_e32 v95, v2
	v_mov_b32_e32 v96, v2
	v_mov_b32_e32 v97, v2
	v_mov_b32_e32 v106, v2
	v_mov_b32_e32 v107, v2
	v_mov_b32_e32 v108, v2
	v_mov_b32_e32 v109, v2
	v_mov_b32_e32 v110, v2
	v_mov_b32_e32 v111, v2
	v_mov_b32_e32 v112, v2
	v_mov_b32_e32 v113, v2
	v_mov_b32_e32 v150, v2
	v_mov_b32_e32 v151, v2
	v_mov_b32_e32 v152, v2
	v_mov_b32_e32 v153, v2
	v_mov_b32_e32 v154, v2
	v_mov_b32_e32 v155, v2
	v_mov_b32_e32 v156, v2
	v_mov_b32_e32 v157, v2
	s_nop 0
	s_nop 0
	s_nop 0
	s_nop 0
	s_nop 0
	s_nop 0
	s_nop 0
	s_nop 0
	s_nop 0
	s_nop 0
	s_nop 0
	s_nop 0
	s_nop 0

; #define WAIT_BAR(N) asm volatile("s_waitcnt vmcnt(" #N ") lgkmcnt(0)\n\ts_barrier":::"memory")
;   #define DMA_K(t,slot) glds16(ksrc+(long)(t)*KVBLK*PQ,(unsigned)__builtin_amdgcn_readfirstlane(kdst+(slot)))
;   #define DMA_V(t,slot) glds16(vsrc+(long)(t)*KVBLK*PQ,(unsigned)__builtin_amdgcn_readfirstlane(vdst+(slot)))
;   #define CMASK(P0,P1,t) do{int jb_=(t)-(NT-4); if(jb_>=-2)cmask(P0,P1,jb_,qrel,hi,tab);}while(0)
;   #define START(P0,P1) do{ const float rm=rowmax(P0,P1); resc=false; \
;     { const float dl=rm; mhat=fadd_s(mhat,dl); \
;       _Pragma("unroll") for(int r=0;r<16;++r){P0[r]=fsub_s(P0[r],dl);P1[r]=fsub_s(P1[r],dl);} \
;       _Pragma("unroll") for(int r=0;r<16;++r)negm[r]=-mhat; asm volatile("":"+v"(negm)); } \
;     _Pragma("unroll") for(int r=0;r<16;++r)P0[r]=__builtin_amdgcn_exp2f(P0[r]); }while(0)
;   #define ROT() do{sl_prev=sl_cur;sl_cur=sl_next;sl_next=(sl_next==(NSLOT-1)*SLOTB)?0:sl_next+SLOTB;}while(0)
;   #define CMASK(P0,P1,t) do{}while(0)
;   #define CMASK(P0,P1,t) do{int jb_=(t)-(NT-4); if(jb_>=-2)cmask(P0,P1,jb_,qrel,hi,tab);}while(0)
; template<int THRL> __device__ __forceinline__ void attn_unit(int b,int qb,const bf16*Q,const bf16*__restrict__ K,const bf16*__restrict__ V,bf16*O,const __attribute__((address_space(3))) float*tab,char*shm){
;     ...
;   f32x16 pA0,pA1,pB0,pB1;
;   int sl_prev=0,sl_cur=0,sl_next=SLOTB;
;     ...
;   DMA_K(2,2*SLOTB);
;   WAIT_BAR(3);
;   qkt(pA0,pA1,Kbase,qr,negm,r32,hi);asm volatile("s_nop 15\n\ts_nop 7":"+v"(pA0),"+v"(pA1));CMASK(pA0,pA1,0);
;   START(pA0,pA1);
;   _Pragma("unroll") for(int r=0;r<16;++r)pA1[r]=__builtin_amdgcn_exp2f(pA1[r]);
;   WAIT_BAR(0);
;   DMA_K(3,0);DMA_V(1,SLOTB);
;   ROT();
;   kload8(kf,kp0+sl_cur);
;   WAIT_BAR(2);
;   s16x4 vlo[8],vhi[8]; u32x4 pw0,pw1,pw2,pw3;
.Lj0_start:
	v_add_f32_e32 v229, v1, v0
	v_sub_f32_e32 v2, v2, v0
	v_sub_f32_e32 v3, v3, v0
	v_sub_f32_e32 v18, v18, v0
	v_sub_f32_e32 v19, v19, v0
	v_sub_f32_e32 v20, v20, v0
	s_nop 0
	v_xor_b32_e32 v48, 0x80000000, v229
	v_mov_b32_e32 v49, v48
	v_mov_b32_e32 v50, v48
	v_mov_b32_e32 v51, v48
	v_mov_b32_e32 v52, v48
	v_mov_b32_e32 v53, v48
	v_mov_b32_e32 v54, v48
	v_mov_b32_e32 v55, v48
	v_mov_b32_e32 v56, v48
	v_mov_b32_e32 v57, v48
	v_mov_b32_e32 v58, v48
	v_mov_b32_e32 v59, v48
	v_mov_b32_e32 v60, v48
	v_mov_b32_e32 v61, v48
	v_mov_b32_e32 v62, v48
	v_mov_b32_e32 v63, v48
	s_waitcnt vmcnt(0) lgkmcnt(0)
	s_barrier
	v_exp_f32_e32 v64, v2
	v_exp_f32_e32 v65, v3
	v_lshl_add_u64 v[2:3], v[204:205], 0, s[36:37]
	s_mov_b32 s7, m0
	s_mov_b32 m0, s97
	s_nop 0
	global_load_lds_dwordx4 v[2:3], off
	s_mov_b32 m0, s7
	s_cselect_b32 s7, 0, 0
	s_add_i32 s6, s7, s6
	v_lshl_add_u64 v[2:3], v[212:213], 0, s[22:23]
	s_add_i32 s6, s6, 0x8000
	s_mov_b32 s7, m0
	s_mov_b32 m0, s6
	s_nop 0
	global_load_lds_dwordx4 v[2:3], off
	s_mov_b32 m0, s7
	ds_read_b128 v[188:191], v231 offset:8192
	ds_read_b128 v[184:187], v231 offset:8704
	ds_read_b128 v[180:183], v231 offset:10240
	ds_read_b128 v[176:179], v231 offset:10752
	ds_read_b128 v[172:175], v231 offset:12288
	ds_read_b128 v[168:171], v231 offset:12800
	ds_read_b128 v[164:167], v231 offset:14336
	ds_read_b128 v[160:163], v231 offset:14848
	v_sub_f32_e32 v4, v4, v0
	v_sub_f32_e32 v21, v21, v0
	v_sub_f32_e32 v5, v5, v0
	v_sub_f32_e32 v22, v22, v0
	v_sub_f32_e32 v6, v6, v0
	v_sub_f32_e32 v23, v23, v0
	v_sub_f32_e32 v7, v7, v0
	v_sub_f32_e32 v24, v24, v0
	v_sub_f32_e32 v8, v8, v0
	v_sub_f32_e32 v25, v25, v0
	v_sub_f32_e32 v9, v9, v0
	v_sub_f32_e32 v26, v26, v0
	v_sub_f32_e32 v10, v10, v0
	v_sub_f32_e32 v27, v27, v0
	v_sub_f32_e32 v11, v11, v0
	v_sub_f32_e32 v28, v28, v0
	v_sub_f32_e32 v12, v12, v0
	v_sub_f32_e32 v29, v29, v0
	v_sub_f32_e32 v13, v13, v0
	v_sub_f32_e32 v30, v30, v0
	v_sub_f32_e32 v14, v14, v0
	v_sub_f32_e32 v31, v31, v0
	v_sub_f32_e32 v15, v15, v0
	v_sub_f32_e32 v32, v32, v0
	v_sub_f32_e32 v16, v16, v0
	v_sub_f32_e32 v33, v33, v0
	v_sub_f32_e32 v0, v17, v0
	v_exp_f32_e32 v80, v18
	v_exp_f32_e32 v81, v19
	v_exp_f32_e32 v82, v20
	v_exp_f32_e32 v83, v21
	v_exp_f32_e32 v84, v22
	v_exp_f32_e32 v85, v23
	v_exp_f32_e32 v86, v24
	v_exp_f32_e32 v87, v25
	v_exp_f32_e32 v88, v26
	v_exp_f32_e32 v89, v27
	v_exp_f32_e32 v90, v28
	v_exp_f32_e32 v91, v29
	v_exp_f32_e32 v92, v30
	v_exp_f32_e32 v93, v31
	v_exp_f32_e32 v94, v32
	v_exp_f32_e32 v95, v33
	v_exp_f32_e32 v66, v4
	v_exp_f32_e32 v67, v5
	v_exp_f32_e32 v68, v6
	v_exp_f32_e32 v69, v7
	v_exp_f32_e32 v70, v8
	v_exp_f32_e32 v71, v9
	v_exp_f32_e32 v72, v10
	v_exp_f32_e32 v73, v11
	v_exp_f32_e32 v74, v12
	v_exp_f32_e32 v75, v13
	v_exp_f32_e32 v76, v14
	v_exp_f32_e32 v77, v15
	v_exp_f32_e32 v78, v16
	v_exp_f32_e32 v79, v0
	s_waitcnt vmcnt(2) lgkmcnt(0)
	s_barrier
	s_andn2_b64 vcc, exec, s[80:81]
	v_cmp_gt_u32_e64 s[6:7], 32, v220
	s_cbranch_vccnz .LBB0_389
	v_mov_b32_e32 v14, v1
	v_mov_b32_e32 v15, v1
	v_mov_b32_e32 v0, v1
	v_mov_b32_e32 v2, v1
	v_mov_b32_e32 v3, v1
	v_mov_b32_e32 v4, v1
	v_mov_b32_e32 v5, v1
	v_mov_b32_e32 v6, v1
	v_mov_b32_e32 v7, v1
	v_mov_b32_e32 v8, v1
	v_mov_b32_e32 v9, v1
	v_mov_b32_e32 v10, v1
	v_mov_b32_e32 v11, v1
	v_mov_b32_e32 v12, v1
	v_mov_b32_e32 v13, v1
	v_mov_b64_e32 v[46:47], v[14:15]
	v_mov_b64_e32 v[30:31], v[14:15]
	v_lshl_add_u64 v[196:197], v[212:213], 0, s[36:37]
	v_lshl_add_u64 v[198:199], v[204:205], 0, s[38:39]
	s_mov_b32 s8, 0
	s_movk_i32 s86, 0x4000
	s_movk_i32 s87, 0x2000
	v_mov_b32_e32 v234, 0
	s_mov_b32 s12, 8
	v_mov_b64_e32 v[44:45], v[12:13]
	v_mov_b64_e32 v[42:43], v[10:11]
	v_mov_b64_e32 v[40:41], v[8:9]
	v_mov_b64_e32 v[38:39], v[6:7]
	v_mov_b64_e32 v[36:37], v[4:5]
	v_mov_b64_e32 v[34:35], v[2:3]
	v_mov_b64_e32 v[32:33], v[0:1]
	v_mov_b64_e32 v[28:29], v[12:13]
	v_mov_b64_e32 v[26:27], v[10:11]
	v_mov_b64_e32 v[24:25], v[8:9]
	v_mov_b64_e32 v[22:23], v[6:7]
	v_mov_b64_e32 v[20:21], v[4:5]
	v_mov_b64_e32 v[18:19], v[2:3]
	v_mov_b64_e32 v[16:17], v[0:1]
	s_bitcmp1_b32 s46, 0
	s_cbranch_scc1 .Lj1_375
	s_nop 0
	s_nop 0
	s_nop 0
	s_nop 0
	s_nop 0
	s_nop 0
	s_nop 0
	s_nop 0

.LBB0_386:
	v_max_f32_e32 v14, v14, v14
	v_max_f32_e32 v14, 0, v14
	v_exp_f32_e64 v15, -v14
	v_add_f32_e32 v229, v229, v14
	v_xor_b32_e32 v48, 0x80000000, v229
	v_mov_b32_e32 v49, v48
	v_mov_b32_e32 v50, v48
	v_mov_b32_e32 v51, v48
	v_mov_b32_e32 v52, v48
	v_mov_b32_e32 v53, v48
	v_mov_b32_e32 v54, v48
	v_mov_b32_e32 v55, v48
	v_mov_b32_e32 v56, v48
	v_mov_b32_e32 v57, v48
	v_mov_b32_e32 v58, v48
	v_mov_b32_e32 v59, v48
	v_mov_b32_e32 v60, v48
	v_mov_b32_e32 v61, v48
	v_mov_b32_e32 v62, v48
	v_mov_b32_e32 v63, v48
	s_and_saveexec_b64 s[84:85], s[6:7]
	ds_write_b32 v228, v15 offset:49152
	s_or_b64 exec, exec, s[84:85]
	v_sub_f32_e32 v95, v95, v14
	v_sub_f32_e32 v94, v94, v14
	v_sub_f32_e32 v93, v93, v14
	v_sub_f32_e32 v92, v92, v14
	v_sub_f32_e32 v91, v91, v14
	v_sub_f32_e32 v90, v90, v14
	v_sub_f32_e32 v89, v89, v14
	v_sub_f32_e32 v88, v88, v14
	v_sub_f32_e32 v87, v87, v14
	v_sub_f32_e32 v86, v86, v14
	v_sub_f32_e32 v85, v85, v14
	v_sub_f32_e32 v84, v84, v14
	v_sub_f32_e32 v83, v83, v14
	v_sub_f32_e32 v82, v82, v14
	v_sub_f32_e32 v81, v81, v14
	v_sub_f32_e32 v80, v80, v14
	v_sub_f32_e32 v79, v79, v14
	v_sub_f32_e32 v78, v78, v14
	v_sub_f32_e32 v77, v77, v14
	v_sub_f32_e32 v76, v76, v14
	v_sub_f32_e32 v75, v75, v14
	v_sub_f32_e32 v74, v74, v14
	v_sub_f32_e32 v73, v73, v14
	v_sub_f32_e32 v72, v72, v14
	v_sub_f32_e32 v71, v71, v14
	v_sub_f32_e32 v70, v70, v14
	v_sub_f32_e32 v69, v69, v14
	v_sub_f32_e32 v68, v68, v14
	v_sub_f32_e32 v67, v67, v14
	v_sub_f32_e32 v66, v66, v14
	v_sub_f32_e32 v65, v65, v14
	v_sub_f32_e32 v64, v64, v14
	v_mul_f32_e32 v234, v234, v15
	s_branch .LBB0_379
	s_nop 0
	s_nop 0
	s_nop 0
	s_nop 0
	s_nop 0
	s_nop 0

; __device__ __forceinline__ void cmask(f32x16&p0,f32x16&p1,int jb,int qrel,int hi,const __attribute__((address_space(3))) float*tab){
;   asm volatile("s_nop 15\n\ts_nop 7":"+v"(p0),"+v"(p1));
;   const __attribute__((address_space(3))) float*tp=tab+(qrel-64*jb-4*hi+256);
.LBB0_397:
	v_lshlrev_b32_e32 v2, 2, v222
	v_add_u32_e32 v0, s29, v2
	v_lshl_or_b32 v2, s26, 7, v2
	v_sub_u32_e32 v2, v2, v233
	s_lshl_b32 s8, s12, 8
	v_subrev_u32_e32 v2, s8, v2
	v_cmp_gt_u32_e64 s[6:7], 32, v220
	v_add_u32_e32 v235, s94, v2
	s_add_i32 s90, s12, 2
	s_lshl_b64 s[84:85], s[12:13], 18
	s_mov_b32 s12, 0
	s_nop 0
	s_nop 0
	s_nop 0
	s_nop 0
	s_nop 0
	s_nop 0

; template <class Epi, class Sched, bool ALIGN_EPI = false, bool SP2 = false>
; __device__ __forceinline__ void gemm_phase(PG8_LAS unsigned char* lds, const Gemm g, const Sched& S, const Epi& E) {
;     ...
;         const char* nA = has_next ? (const char*)g.A + (size_t)nxt.pm * tstep : cA; const char* nB = has_next ? (const char*)g.Bt + (size_t)nxt.pn * tstep : cB;
;         for (int t = 0; t < nt; t += 2) {
;             const bool last = (t == nt - 2);
;             const char* a1 = cA + (size_t)(t + 1) * kstep;
;             const char* a2 = last ? nA : cA + (size_t)(t + 2) * kstep; const char* b2 = last ? nB : cB + (size_t)(t + 2) * kstep;
;     ...
;         for (int a = 0; a < 2; ++a)
; #pragma unroll
;             for (int b = 0; b < 2; ++b)
; #pragma unroll
;                 for (int m = 0; m < 4; ++m)
; #pragma unroll
;                     for (int n = 0; n < 2; ++n) acc[a][b][m][n] = (f32x4){0.f, 0.f, 0.f, 0.f};
.LBB0_467:
	s_ashr_i32 s75, s74, 31
	s_lshl_b64 s[76:77], s[74:75], 19
	s_add_u32 s76, s44, s76
	s_addc_u32 s77, s9, s77
	s_and_b64 s[78:79], s[4:5], exec
	s_cselect_b32 s75, s77, s81
	s_cselect_b32 s92, s76, s80
	s_ashr_i32 s73, s72, 31
	s_lshl_b64 s[78:79], s[72:73], 19
	s_add_u32 s78, s46, s78
	s_addc_u32 s79, s45, s79
	s_and_b64 s[84:85], s[4:5], exec
	s_cselect_b32 s73, s79, s83
	s_cselect_b32 s93, s78, s82
	s_add_u32 s80, s80, 0x40080
	s_addc_u32 s81, s81, 0
	s_add_u32 s94, s82, 0x100
	v_mov_b32_e32 v2, 0
	s_addc_u32 s95, s83, 0
	s_mov_b32 s96, -2
	v_mov_b32_e32 v3, v2
	v_mov_b32_e32 v4, v2
	v_mov_b32_e32 v5, v2
	v_mov_b32_e32 v6, v2
	v_mov_b32_e32 v7, v2
	v_mov_b32_e32 v8, v2
	v_mov_b32_e32 v9, v2
	v_mov_b32_e32 v10, v2
	v_mov_b32_e32 v11, v2
	v_mov_b32_e32 v12, v2
	v_mov_b32_e32 v13, v2
	v_mov_b32_e32 v18, v2
	v_mov_b32_e32 v19, v2
	v_mov_b32_e32 v20, v2
	v_mov_b32_e32 v21, v2
	v_mov_b32_e32 v26, v2
	v_mov_b32_e32 v27, v2
	v_mov_b32_e32 v28, v2
	v_mov_b32_e32 v29, v2
	v_mov_b32_e32 v34, v2
	v_mov_b32_e32 v35, v2
	v_mov_b32_e32 v36, v2
	v_mov_b32_e32 v37, v2
	v_mov_b32_e32 v42, v2
	v_mov_b32_e32 v43, v2
	v_mov_b32_e32 v44, v2
	v_mov_b32_e32 v45, v2
	v_mov_b32_e32 v50, v2
	v_mov_b32_e32 v51, v2
	v_mov_b32_e32 v52, v2
	v_mov_b32_e32 v53, v2
	v_mov_b32_e32 v14, v2
	v_mov_b32_e32 v15, v2
	v_mov_b32_e32 v16, v2
	v_mov_b32_e32 v17, v2
	v_mov_b32_e32 v22, v2
	v_mov_b32_e32 v23, v2
	v_mov_b32_e32 v24, v2
	v_mov_b32_e32 v25, v2
	v_mov_b32_e32 v30, v2
	v_mov_b32_e32 v31, v2
	v_mov_b32_e32 v32, v2
	v_mov_b32_e32 v33, v2
	v_mov_b32_e32 v38, v2
	v_mov_b32_e32 v39, v2
	v_mov_b32_e32 v40, v2
	v_mov_b32_e32 v41, v2
	v_mov_b32_e32 v46, v2
	v_mov_b32_e32 v47, v2
	v_mov_b32_e32 v48, v2
	v_mov_b32_e32 v49, v2
	v_mov_b32_e32 v54, v2
	v_mov_b32_e32 v55, v2
	v_mov_b32_e32 v56, v2
	v_mov_b32_e32 v57, v2
	v_mov_b32_e32 v58, v2
	v_mov_b32_e32 v59, v2
	v_mov_b32_e32 v60, v2
	v_mov_b32_e32 v61, v2
	v_mov_b32_e32 v62, v2
	v_mov_b32_e32 v63, v2
	v_mov_b32_e32 v64, v2
	v_mov_b32_e32 v65, v2
	v_mov_b32_e32 v66, v2
	v_mov_b32_e32 v67, v2
	v_mov_b32_e32 v68, v2
	v_mov_b32_e32 v69, v2
	v_mov_b32_e32 v70, v2
	v_mov_b32_e32 v71, v2
	v_mov_b32_e32 v72, v2
	v_mov_b32_e32 v73, v2
	v_mov_b32_e32 v74, v2
	v_mov_b32_e32 v75, v2
	v_mov_b32_e32 v76, v2
	v_mov_b32_e32 v77, v2
	v_mov_b32_e32 v82, v2
	v_mov_b32_e32 v83, v2
	v_mov_b32_e32 v84, v2
	v_mov_b32_e32 v85, v2
	v_mov_b32_e32 v90, v2
	v_mov_b32_e32 v91, v2
	v_mov_b32_e32 v92, v2
	v_mov_b32_e32 v93, v2
	v_mov_b32_e32 v98, v2
	v_mov_b32_e32 v99, v2
	v_mov_b32_e32 v100, v2
	v_mov_b32_e32 v101, v2
	v_mov_b32_e32 v106, v2
	v_mov_b32_e32 v107, v2
	v_mov_b32_e32 v108, v2
	v_mov_b32_e32 v109, v2
	v_mov_b32_e32 v114, v2
	v_mov_b32_e32 v115, v2
	v_mov_b32_e32 v116, v2
	v_mov_b32_e32 v117, v2
	v_mov_b32_e32 v78, v2
	v_mov_b32_e32 v79, v2
	v_mov_b32_e32 v80, v2
	v_mov_b32_e32 v81, v2
	v_mov_b32_e32 v86, v2
	v_mov_b32_e32 v87, v2
	v_mov_b32_e32 v88, v2
	v_mov_b32_e32 v89, v2
	v_mov_b32_e32 v94, v2
	v_mov_b32_e32 v95, v2
	v_mov_b32_e32 v96, v2
	v_mov_b32_e32 v97, v2
	v_mov_b32_e32 v102, v2
	v_mov_b32_e32 v103, v2
	v_mov_b32_e32 v104, v2
	v_mov_b32_e32 v105, v2
	v_mov_b32_e32 v110, v2
	v_mov_b32_e32 v111, v2
	v_mov_b32_e32 v112, v2
	v_mov_b32_e32 v113, v2
	v_mov_b32_e32 v118, v2
	v_mov_b32_e32 v119, v2
	v_mov_b32_e32 v120, v2
	v_mov_b32_e32 v121, v2
	v_mov_b32_e32 v122, v2
	v_mov_b32_e32 v123, v2
	v_mov_b32_e32 v124, v2
	v_mov_b32_e32 v125, v2
	v_mov_b32_e32 v126, v2
	v_mov_b32_e32 v127, v2
	v_mov_b32_e32 v128, v2
	v_mov_b32_e32 v129, v2
	s_nop 0
	s_nop 0
	s_nop 0
	s_nop 0
	s_nop 0
	s_nop 0
	s_nop 0
	s_nop 0
	s_nop 0
	s_nop 0
	s_nop 0
	s_nop 0
	s_nop 0
	s_nop 0

; __global__ void __launch_bounds__(NWAVES * 64, 2) trunk_fwd(Args args) {
;     ...
;                 for (int i = 0; S.next(i, xu); ++i) { const int tm = xu.pm, h = xu.pn, b = tm >> 4;
;     ...
;                     xat::unit(L, BIG + (size_t)tm * 256 * 1024 + h * 256, KB + (size_t)b * 256 * 4096 + l * 1024 + h * 256, VT + (size_t)(l * 1024 + h * 256) * 4096 + b * 256, MIX + (size_t)tm * 256 * 1024 + h * 256);
.LBB0_585:
	s_andn2_b64 vcc, exec, s[4:5]
	s_cbranch_vccz .LBB0_600
	s_nop 0
	s_nop 0
	s_nop 0
	s_nop 0
